# P4 epilogue: (n=0,n=1) tiles swapped between lane pairs so x loads and out stores move 8 rows x 128B full lines per instruction; acc and gate pre-swapped, same fma per element
# speedup vs baseline: 1.0552x; 1.0180x over previous
; #define EO_LOAD(bt_) do { _Pragma("unroll") for (int mm = 0; mm < 2; ++mm) { const float* xr = xbase + (size_t)(row0 + ((bt_) >> 1) * 128 + (2 * ((bt_) & 1) + mm) * 16) * DM + col0; \
;             _Pragma("unroll") for (int bj = 0; bj < 2; ++bj) _Pragma("unroll") for (int n = 0; n < 2; ++n) xv[(bt_) & 1][mm][bj][n] = *(const f32x4*)(xr + 128 * bj + 4 * n); } } while (0)
; #define EO_FENCE() asm volatile("" ::: "memory")
;     __device__ __forceinline__ void operator()(const f32x4 (&acc)[2][2][4][2], const pg8::Unit& u, int wr, int wc, int fr, int fq) const {
;         const int row0 = u.pm * 256 + wr * 64 + fr, col0 = u.pn * 256 + wc * 32 + 8 * fq;
;         const int s = (u.pm * 256 < NP) ? ((u.pm * 256) >> 12) : 16;
;         const float* gate = mod + s * 3072 + 2048;
;         f32x4 gv[2][2];
; #pragma unroll
;         for (int bj = 0; bj < 2; ++bj)
; #pragma unroll
;             for (int n = 0; n < 2; ++n) gv[bj][n] = *(const f32x4*)(gate + col0 + 128 * bj + 4 * n);
;         const float* xbase = (u.pm * 256 < NP) ? xp : xs - (size_t)NP * DM;
;         f32x4 xv[2][2][2][2];
;     ...
;         EO_LOAD(0); EO_FENCE(); EO_LOAD(1); EO_FENCE();
;         EO_STORE(0); EO_FENCE(); EO_LOAD(2); EO_FENCE();
;         EO_STORE(1); EO_FENCE(); EO_LOAD(3); EO_FENCE();
;         EO_STORE(2); EO_FENCE(); EO_STORE(3);
.LBB0_460:
	s_add_u32 s68, s61, 0x40080
	s_addc_u32 s69, s25, 0
	v_lshl_add_u64 v[164:165], s[68:69], 0, v[152:153]
	s_add_i32 m0, s31, 0xc000
	v_lshl_add_u64 v[216:217], s[68:69], 0, v[154:155]
	global_load_lds_dwordx4 v[164:165], off
	s_add_i32 m0, s31, 0xe000
	s_nop 0
	global_load_lds_dwordx4 v[216:217], off
	s_lshr_b32 s21, s30, 4
	s_cmpk_lt_i32 s30, 0x100
	s_mulk_i32 s21, 0xc00
	s_cselect_b32 s34, s21, 0xc000
	s_cselect_b32 s38, s36, s54
	s_cselect_b32 s39, s37, s55
	s_ashr_i32 s35, s34, 31
	v_lshl_or_b32 v128, s60, 8, v168
	s_lshl_b64 s[34:35], s[34:35], 2
	s_add_u32 s34, s22, s34
	v_ashrrev_i32_e32 v129, 31, v128
	v_lshl_add_u32 v220, s30, 8, v166
	v_and_b32_e32 v220, -2, v220
	s_addc_u32 s35, s23, s35
	v_lshlrev_b64 v[160:161], 2, v[128:129]
	v_or_b32_e32 v188, 16, v220
	v_lshl_add_u64 v[128:129], s[34:35], 0, v[160:161]
	v_ashrrev_i32_e32 v221, 31, v220
	v_ashrrev_i32_e32 v189, 31, v188
	v_or_b32_e32 v204, 32, v220
	v_lshl_add_u64 v[132:133], v[128:129], 0, s[10:11]
	v_add_co_u32_e32 v128, vcc, s52, v128
	v_and_b32_e32 v162, 1, v166
	v_lshlrev_b32_e32 v162, 4, v162
	v_add_u32_e32 v162, 0x800, v162
	v_add_u32_e32 v160, v160, v162
	v_lshl_add_u64 v[162:163], s[38:39], 0, v[160:161]
	v_lshlrev_b64 v[164:165], 12, v[220:221]
	v_lshlrev_b64 v[236:237], 12, v[188:189]
	v_ashrrev_i32_e32 v205, 31, v204
	v_addc_co_u32_e32 v129, vcc, 0, v129, vcc
	v_lshl_add_u64 v[184:185], v[162:163], 0, v[164:165]
	v_lshl_add_u64 v[200:201], v[162:163], 0, v[236:237]
	v_lshlrev_b64 v[238:239], 12, v[204:205]
	global_load_dwordx4 v[136:139], v[128:129], off
	s_nop 0
	global_load_dwordx4 v[128:131], v[132:133], off offset:528
	global_load_dwordx4 v[172:175], v[184:185], off offset:2048
	global_load_dwordx4 v[176:179], v[184:185], off offset:-2048
	global_load_dwordx4 v[140:143], v[132:133], off offset:16
	s_nop 0
	global_load_dwordx4 v[132:135], v[132:133], off offset:512
	s_nop 0
	global_load_dwordx4 v[180:183], v[184:185], off offset:2560
	s_nop 0
	global_load_dwordx4 v[184:187], v[184:185], off offset:-1536
	s_nop 0
	global_load_dwordx4 v[188:191], v[200:201], off offset:-2048
	global_load_dwordx4 v[192:195], v[200:201], off offset:2048
	global_load_dwordx4 v[196:199], v[200:201], off offset:-1536
	s_nop 0
	global_load_dwordx4 v[200:203], v[200:201], off offset:2560
	v_lshl_add_u64 v[216:217], v[162:163], 0, v[238:239]
	v_or_b32_e32 v220, 48, v220
	global_load_dwordx4 v[204:207], v[216:217], off offset:-2048
	global_load_dwordx4 v[208:211], v[216:217], off offset:2048
	global_load_dwordx4 v[212:215], v[216:217], off offset:-1536
	s_nop 0
	global_load_dwordx4 v[216:219], v[216:217], off offset:2560
	v_ashrrev_i32_e32 v221, 31, v220
	v_lshlrev_b64 v[240:241], 12, v[220:221]
	v_lshl_add_u64 v[232:233], v[162:163], 0, v[240:241]
	global_load_dwordx4 v[220:223], v[232:233], off offset:-2048
	global_load_dwordx4 v[224:227], v[232:233], off offset:2048
	global_load_dwordx4 v[228:231], v[232:233], off offset:-1536
	s_nop 0
	global_load_dwordx4 v[232:235], v[232:233], off offset:2560
	v_lshl_add_u64 v[242:243], s[66:67], 0, v[164:165]
	v_lshl_add_u64 v[242:243], v[242:243], 0, v[160:161]
	v_lshl_add_u64 v[236:237], s[66:67], 0, v[236:237]
	v_lshl_add_u64 v[244:245], v[164:165], 0, s[12:13]
	v_lshl_add_u64 v[236:237], v[236:237], 0, v[160:161]
	v_lshl_add_u64 v[246:247], v[162:163], 0, v[244:245]
	s_andn2_b64 s[74:75], exec, s[0:1]
	s_mov_b64 s[0:1], -1
	s_mov_b32 vcc_lo, 0x55555555
	s_mov_b32 vcc_hi, 0x55555555
	v_mov_b32_dpp v248, v124 quad_perm:[1,0,3,2] row_mask:0xf bank_mask:0xf
	v_cndmask_b32_dpp v124, v120, v124, vcc quad_perm:[1,0,3,2] row_mask:0xf bank_mask:0xf
	v_cndmask_b32_e32 v120, v120, v248, vcc
	v_mov_b32_dpp v249, v125 quad_perm:[1,0,3,2] row_mask:0xf bank_mask:0xf
	v_cndmask_b32_dpp v125, v121, v125, vcc quad_perm:[1,0,3,2] row_mask:0xf bank_mask:0xf
	v_cndmask_b32_e32 v121, v121, v249, vcc
	v_mov_b32_dpp v248, v126 quad_perm:[1,0,3,2] row_mask:0xf bank_mask:0xf
	v_cndmask_b32_dpp v126, v122, v126, vcc quad_perm:[1,0,3,2] row_mask:0xf bank_mask:0xf
	v_cndmask_b32_e32 v122, v122, v248, vcc
	v_mov_b32_dpp v249, v127 quad_perm:[1,0,3,2] row_mask:0xf bank_mask:0xf
	v_cndmask_b32_dpp v127, v123, v127, vcc quad_perm:[1,0,3,2] row_mask:0xf bank_mask:0xf
	v_cndmask_b32_e32 v123, v123, v249, vcc
	v_mov_b32_dpp v248, v108 quad_perm:[1,0,3,2] row_mask:0xf bank_mask:0xf
	v_cndmask_b32_dpp v108, v104, v108, vcc quad_perm:[1,0,3,2] row_mask:0xf bank_mask:0xf
	v_cndmask_b32_e32 v104, v104, v248, vcc
	v_mov_b32_dpp v249, v109 quad_perm:[1,0,3,2] row_mask:0xf bank_mask:0xf
	v_cndmask_b32_dpp v109, v105, v109, vcc quad_perm:[1,0,3,2] row_mask:0xf bank_mask:0xf
	v_cndmask_b32_e32 v105, v105, v249, vcc
	v_mov_b32_dpp v248, v110 quad_perm:[1,0,3,2] row_mask:0xf bank_mask:0xf
	v_cndmask_b32_dpp v110, v106, v110, vcc quad_perm:[1,0,3,2] row_mask:0xf bank_mask:0xf
	v_cndmask_b32_e32 v106, v106, v248, vcc
	v_mov_b32_dpp v249, v111 quad_perm:[1,0,3,2] row_mask:0xf bank_mask:0xf
	v_cndmask_b32_dpp v111, v107, v111, vcc quad_perm:[1,0,3,2] row_mask:0xf bank_mask:0xf
	v_cndmask_b32_e32 v107, v107, v249, vcc
	v_mov_b32_dpp v248, v116 quad_perm:[1,0,3,2] row_mask:0xf bank_mask:0xf
	v_cndmask_b32_dpp v116, v112, v116, vcc quad_perm:[1,0,3,2] row_mask:0xf bank_mask:0xf
	v_cndmask_b32_e32 v112, v112, v248, vcc
	v_mov_b32_dpp v249, v117 quad_perm:[1,0,3,2] row_mask:0xf bank_mask:0xf
	v_cndmask_b32_dpp v117, v113, v117, vcc quad_perm:[1,0,3,2] row_mask:0xf bank_mask:0xf
	v_cndmask_b32_e32 v113, v113, v249, vcc
	v_mov_b32_dpp v248, v118 quad_perm:[1,0,3,2] row_mask:0xf bank_mask:0xf
	v_cndmask_b32_dpp v118, v114, v118, vcc quad_perm:[1,0,3,2] row_mask:0xf bank_mask:0xf
; #define EO_LOAD(bt_) do { _Pragma("unroll") for (int mm = 0; mm < 2; ++mm) { const float* xr = xbase + (size_t)(row0 + ((bt_) >> 1) * 128 + (2 * ((bt_) & 1) + mm) * 16) * DM + col0; \
;             _Pragma("unroll") for (int bj = 0; bj < 2; ++bj) _Pragma("unroll") for (int n = 0; n < 2; ++n) xv[(bt_) & 1][mm][bj][n] = *(const f32x4*)(xr + 128 * bj + 4 * n); } } while (0)
; #define EO_FENCE() asm volatile("" ::: "memory")
;     __device__ __forceinline__ void operator()(const f32x4 (&acc)[2][2][4][2], const pg8::Unit& u, int wr, int wc, int fr, int fq) const {
;     ...
;         EO_LOAD(0); EO_FENCE(); EO_LOAD(1); EO_FENCE();
;         EO_STORE(0); EO_FENCE(); EO_LOAD(2); EO_FENCE();
;         EO_STORE(1); EO_FENCE(); EO_LOAD(3); EO_FENCE();
;         EO_STORE(2); EO_FENCE(); EO_STORE(3);
	v_cndmask_b32_e32 v114, v114, v248, vcc
	v_mov_b32_dpp v249, v119 quad_perm:[1,0,3,2] row_mask:0xf bank_mask:0xf
	v_cndmask_b32_dpp v119, v115, v119, vcc quad_perm:[1,0,3,2] row_mask:0xf bank_mask:0xf
	v_cndmask_b32_e32 v115, v115, v249, vcc
	v_mov_b32_dpp v248, v100 quad_perm:[1,0,3,2] row_mask:0xf bank_mask:0xf
	v_cndmask_b32_dpp v100, v92, v100, vcc quad_perm:[1,0,3,2] row_mask:0xf bank_mask:0xf
	v_cndmask_b32_e32 v92, v92, v248, vcc
	v_mov_b32_dpp v249, v101 quad_perm:[1,0,3,2] row_mask:0xf bank_mask:0xf
	v_cndmask_b32_dpp v101, v93, v101, vcc quad_perm:[1,0,3,2] row_mask:0xf bank_mask:0xf
	v_cndmask_b32_e32 v93, v93, v249, vcc
	v_mov_b32_dpp v248, v102 quad_perm:[1,0,3,2] row_mask:0xf bank_mask:0xf
	v_cndmask_b32_dpp v102, v94, v102, vcc quad_perm:[1,0,3,2] row_mask:0xf bank_mask:0xf
	v_cndmask_b32_e32 v94, v94, v248, vcc
	v_mov_b32_dpp v249, v103 quad_perm:[1,0,3,2] row_mask:0xf bank_mask:0xf
	v_cndmask_b32_dpp v103, v95, v103, vcc quad_perm:[1,0,3,2] row_mask:0xf bank_mask:0xf
	v_cndmask_b32_e32 v95, v95, v249, vcc
	v_mov_b32_dpp v248, v96 quad_perm:[1,0,3,2] row_mask:0xf bank_mask:0xf
	v_cndmask_b32_dpp v96, v88, v96, vcc quad_perm:[1,0,3,2] row_mask:0xf bank_mask:0xf
	v_cndmask_b32_e32 v88, v88, v248, vcc
	v_mov_b32_dpp v249, v97 quad_perm:[1,0,3,2] row_mask:0xf bank_mask:0xf
	v_cndmask_b32_dpp v97, v89, v97, vcc quad_perm:[1,0,3,2] row_mask:0xf bank_mask:0xf
	v_cndmask_b32_e32 v89, v89, v249, vcc
	v_mov_b32_dpp v248, v98 quad_perm:[1,0,3,2] row_mask:0xf bank_mask:0xf
	v_cndmask_b32_dpp v98, v90, v98, vcc quad_perm:[1,0,3,2] row_mask:0xf bank_mask:0xf
	v_cndmask_b32_e32 v90, v90, v248, vcc
	v_mov_b32_dpp v249, v99 quad_perm:[1,0,3,2] row_mask:0xf bank_mask:0xf
	v_cndmask_b32_dpp v99, v91, v99, vcc quad_perm:[1,0,3,2] row_mask:0xf bank_mask:0xf
	v_cndmask_b32_e32 v91, v91, v249, vcc
	v_mov_b32_dpp v248, v80 quad_perm:[1,0,3,2] row_mask:0xf bank_mask:0xf
	v_cndmask_b32_dpp v80, v72, v80, vcc quad_perm:[1,0,3,2] row_mask:0xf bank_mask:0xf
	v_cndmask_b32_e32 v72, v72, v248, vcc
	v_mov_b32_dpp v249, v81 quad_perm:[1,0,3,2] row_mask:0xf bank_mask:0xf
	v_cndmask_b32_dpp v81, v73, v81, vcc quad_perm:[1,0,3,2] row_mask:0xf bank_mask:0xf
	v_cndmask_b32_e32 v73, v73, v249, vcc
	v_mov_b32_dpp v248, v82 quad_perm:[1,0,3,2] row_mask:0xf bank_mask:0xf
	v_cndmask_b32_dpp v82, v74, v82, vcc quad_perm:[1,0,3,2] row_mask:0xf bank_mask:0xf
	v_cndmask_b32_e32 v74, v74, v248, vcc
	v_mov_b32_dpp v249, v83 quad_perm:[1,0,3,2] row_mask:0xf bank_mask:0xf
	v_cndmask_b32_dpp v83, v75, v83, vcc quad_perm:[1,0,3,2] row_mask:0xf bank_mask:0xf
	v_cndmask_b32_e32 v75, v75, v249, vcc
	v_mov_b32_dpp v248, v84 quad_perm:[1,0,3,2] row_mask:0xf bank_mask:0xf
	v_cndmask_b32_dpp v84, v76, v84, vcc quad_perm:[1,0,3,2] row_mask:0xf bank_mask:0xf
	v_cndmask_b32_e32 v76, v76, v248, vcc
	v_mov_b32_dpp v249, v85 quad_perm:[1,0,3,2] row_mask:0xf bank_mask:0xf
	v_cndmask_b32_dpp v85, v77, v85, vcc quad_perm:[1,0,3,2] row_mask:0xf bank_mask:0xf
	v_cndmask_b32_e32 v77, v77, v249, vcc
	v_mov_b32_dpp v248, v86 quad_perm:[1,0,3,2] row_mask:0xf bank_mask:0xf
	v_cndmask_b32_dpp v86, v78, v86, vcc quad_perm:[1,0,3,2] row_mask:0xf bank_mask:0xf
	v_cndmask_b32_e32 v78, v78, v248, vcc
	v_mov_b32_dpp v249, v87 quad_perm:[1,0,3,2] row_mask:0xf bank_mask:0xf
	v_cndmask_b32_dpp v87, v79, v87, vcc quad_perm:[1,0,3,2] row_mask:0xf bank_mask:0xf
	v_cndmask_b32_e32 v79, v79, v249, vcc
	v_mov_b32_dpp v248, v68 quad_perm:[1,0,3,2] row_mask:0xf bank_mask:0xf
	v_cndmask_b32_dpp v68, v64, v68, vcc quad_perm:[1,0,3,2] row_mask:0xf bank_mask:0xf
	v_cndmask_b32_e32 v64, v64, v248, vcc
	v_mov_b32_dpp v249, v69 quad_perm:[1,0,3,2] row_mask:0xf bank_mask:0xf
	v_cndmask_b32_dpp v69, v65, v69, vcc quad_perm:[1,0,3,2] row_mask:0xf bank_mask:0xf
	v_cndmask_b32_e32 v65, v65, v249, vcc
	v_mov_b32_dpp v248, v70 quad_perm:[1,0,3,2] row_mask:0xf bank_mask:0xf
	v_cndmask_b32_dpp v70, v66, v70, vcc quad_perm:[1,0,3,2] row_mask:0xf bank_mask:0xf
	v_cndmask_b32_e32 v66, v66, v248, vcc
	v_mov_b32_dpp v249, v71 quad_perm:[1,0,3,2] row_mask:0xf bank_mask:0xf
	v_cndmask_b32_dpp v71, v67, v71, vcc quad_perm:[1,0,3,2] row_mask:0xf bank_mask:0xf
	v_cndmask_b32_e32 v67, v67, v249, vcc
	v_mov_b32_dpp v248, v60 quad_perm:[1,0,3,2] row_mask:0xf bank_mask:0xf
	v_cndmask_b32_dpp v60, v56, v60, vcc quad_perm:[1,0,3,2] row_mask:0xf bank_mask:0xf
	v_cndmask_b32_e32 v56, v56, v248, vcc
	v_mov_b32_dpp v249, v61 quad_perm:[1,0,3,2] row_mask:0xf bank_mask:0xf
	v_cndmask_b32_dpp v61, v57, v61, vcc quad_perm:[1,0,3,2] row_mask:0xf bank_mask:0xf
	v_cndmask_b32_e32 v57, v57, v249, vcc
	v_mov_b32_dpp v248, v62 quad_perm:[1,0,3,2] row_mask:0xf bank_mask:0xf
	v_cndmask_b32_dpp v62, v58, v62, vcc quad_perm:[1,0,3,2] row_mask:0xf bank_mask:0xf
	v_cndmask_b32_e32 v58, v58, v248, vcc
	v_mov_b32_dpp v249, v63 quad_perm:[1,0,3,2] row_mask:0xf bank_mask:0xf
	v_cndmask_b32_dpp v63, v59, v63, vcc quad_perm:[1,0,3,2] row_mask:0xf bank_mask:0xf
	v_cndmask_b32_e32 v59, v59, v249, vcc
	v_mov_b32_dpp v248, v44 quad_perm:[1,0,3,2] row_mask:0xf bank_mask:0xf
	v_cndmask_b32_dpp v44, v40, v44, vcc quad_perm:[1,0,3,2] row_mask:0xf bank_mask:0xf
	v_cndmask_b32_e32 v40, v40, v248, vcc
	v_mov_b32_dpp v249, v45 quad_perm:[1,0,3,2] row_mask:0xf bank_mask:0xf
	v_cndmask_b32_dpp v45, v41, v45, vcc quad_perm:[1,0,3,2] row_mask:0xf bank_mask:0xf
	v_cndmask_b32_e32 v41, v41, v249, vcc
	v_mov_b32_dpp v248, v46 quad_perm:[1,0,3,2] row_mask:0xf bank_mask:0xf
	v_cndmask_b32_dpp v46, v42, v46, vcc quad_perm:[1,0,3,2] row_mask:0xf bank_mask:0xf
	v_cndmask_b32_e32 v42, v42, v248, vcc
	v_mov_b32_dpp v249, v47 quad_perm:[1,0,3,2] row_mask:0xf bank_mask:0xf
; #define EO_LOAD(bt_) do { _Pragma("unroll") for (int mm = 0; mm < 2; ++mm) { const float* xr = xbase + (size_t)(row0 + ((bt_) >> 1) * 128 + (2 * ((bt_) & 1) + mm) * 16) * DM + col0; \
;             _Pragma("unroll") for (int bj = 0; bj < 2; ++bj) _Pragma("unroll") for (int n = 0; n < 2; ++n) xv[(bt_) & 1][mm][bj][n] = *(const f32x4*)(xr + 128 * bj + 4 * n); } } while (0)
; #define EO_FENCE() asm volatile("" ::: "memory")
;     __device__ __forceinline__ void operator()(const f32x4 (&acc)[2][2][4][2], const pg8::Unit& u, int wr, int wc, int fr, int fq) const {
;     ...
;         EO_LOAD(0); EO_FENCE(); EO_LOAD(1); EO_FENCE();
;         EO_STORE(0); EO_FENCE(); EO_LOAD(2); EO_FENCE();
;         EO_STORE(1); EO_FENCE(); EO_LOAD(3); EO_FENCE();
;         EO_STORE(2); EO_FENCE(); EO_STORE(3);
	v_cndmask_b32_dpp v47, v43, v47, vcc quad_perm:[1,0,3,2] row_mask:0xf bank_mask:0xf
	v_cndmask_b32_e32 v43, v43, v249, vcc
	v_mov_b32_dpp v248, v52 quad_perm:[1,0,3,2] row_mask:0xf bank_mask:0xf
	v_cndmask_b32_dpp v52, v48, v52, vcc quad_perm:[1,0,3,2] row_mask:0xf bank_mask:0xf
	v_cndmask_b32_e32 v48, v48, v248, vcc
	v_mov_b32_dpp v249, v53 quad_perm:[1,0,3,2] row_mask:0xf bank_mask:0xf
	v_cndmask_b32_dpp v53, v49, v53, vcc quad_perm:[1,0,3,2] row_mask:0xf bank_mask:0xf
	v_cndmask_b32_e32 v49, v49, v249, vcc
	v_mov_b32_dpp v248, v54 quad_perm:[1,0,3,2] row_mask:0xf bank_mask:0xf
	v_cndmask_b32_dpp v54, v50, v54, vcc quad_perm:[1,0,3,2] row_mask:0xf bank_mask:0xf
	v_cndmask_b32_e32 v50, v50, v248, vcc
	v_mov_b32_dpp v249, v55 quad_perm:[1,0,3,2] row_mask:0xf bank_mask:0xf
	v_cndmask_b32_dpp v55, v51, v55, vcc quad_perm:[1,0,3,2] row_mask:0xf bank_mask:0xf
	v_cndmask_b32_e32 v51, v51, v249, vcc
	v_mov_b32_dpp v248, v32 quad_perm:[1,0,3,2] row_mask:0xf bank_mask:0xf
	v_cndmask_b32_dpp v32, v28, v32, vcc quad_perm:[1,0,3,2] row_mask:0xf bank_mask:0xf
	v_cndmask_b32_e32 v28, v28, v248, vcc
	v_mov_b32_dpp v249, v33 quad_perm:[1,0,3,2] row_mask:0xf bank_mask:0xf
	v_cndmask_b32_dpp v33, v29, v33, vcc quad_perm:[1,0,3,2] row_mask:0xf bank_mask:0xf
	v_cndmask_b32_e32 v29, v29, v249, vcc
	v_mov_b32_dpp v248, v34 quad_perm:[1,0,3,2] row_mask:0xf bank_mask:0xf
	v_cndmask_b32_dpp v34, v30, v34, vcc quad_perm:[1,0,3,2] row_mask:0xf bank_mask:0xf
	v_cndmask_b32_e32 v30, v30, v248, vcc
	v_mov_b32_dpp v249, v35 quad_perm:[1,0,3,2] row_mask:0xf bank_mask:0xf
	v_cndmask_b32_dpp v35, v31, v35, vcc quad_perm:[1,0,3,2] row_mask:0xf bank_mask:0xf
	v_cndmask_b32_e32 v31, v31, v249, vcc
	v_mov_b32_dpp v248, v36 quad_perm:[1,0,3,2] row_mask:0xf bank_mask:0xf
	v_cndmask_b32_dpp v36, v24, v36, vcc quad_perm:[1,0,3,2] row_mask:0xf bank_mask:0xf
	v_cndmask_b32_e32 v24, v24, v248, vcc
	v_mov_b32_dpp v249, v37 quad_perm:[1,0,3,2] row_mask:0xf bank_mask:0xf
	v_cndmask_b32_dpp v37, v25, v37, vcc quad_perm:[1,0,3,2] row_mask:0xf bank_mask:0xf
	v_cndmask_b32_e32 v25, v25, v249, vcc
	v_mov_b32_dpp v248, v38 quad_perm:[1,0,3,2] row_mask:0xf bank_mask:0xf
	v_cndmask_b32_dpp v38, v26, v38, vcc quad_perm:[1,0,3,2] row_mask:0xf bank_mask:0xf
	v_cndmask_b32_e32 v26, v26, v248, vcc
	v_mov_b32_dpp v249, v39 quad_perm:[1,0,3,2] row_mask:0xf bank_mask:0xf
	v_cndmask_b32_dpp v39, v27, v39, vcc quad_perm:[1,0,3,2] row_mask:0xf bank_mask:0xf
	v_cndmask_b32_e32 v27, v27, v249, vcc
	v_mov_b32_dpp v248, v16 quad_perm:[1,0,3,2] row_mask:0xf bank_mask:0xf
	v_cndmask_b32_dpp v16, v8, v16, vcc quad_perm:[1,0,3,2] row_mask:0xf bank_mask:0xf
	v_cndmask_b32_e32 v8, v8, v248, vcc
	v_mov_b32_dpp v249, v17 quad_perm:[1,0,3,2] row_mask:0xf bank_mask:0xf
	v_cndmask_b32_dpp v17, v9, v17, vcc quad_perm:[1,0,3,2] row_mask:0xf bank_mask:0xf
	v_cndmask_b32_e32 v9, v9, v249, vcc
	v_mov_b32_dpp v248, v18 quad_perm:[1,0,3,2] row_mask:0xf bank_mask:0xf
	v_cndmask_b32_dpp v18, v10, v18, vcc quad_perm:[1,0,3,2] row_mask:0xf bank_mask:0xf
	v_cndmask_b32_e32 v10, v10, v248, vcc
	v_mov_b32_dpp v249, v19 quad_perm:[1,0,3,2] row_mask:0xf bank_mask:0xf
	v_cndmask_b32_dpp v19, v11, v19, vcc quad_perm:[1,0,3,2] row_mask:0xf bank_mask:0xf
	v_cndmask_b32_e32 v11, v11, v249, vcc
	v_mov_b32_dpp v248, v20 quad_perm:[1,0,3,2] row_mask:0xf bank_mask:0xf
	v_cndmask_b32_dpp v20, v12, v20, vcc quad_perm:[1,0,3,2] row_mask:0xf bank_mask:0xf
	v_cndmask_b32_e32 v12, v12, v248, vcc
	v_mov_b32_dpp v249, v21 quad_perm:[1,0,3,2] row_mask:0xf bank_mask:0xf
	v_cndmask_b32_dpp v21, v13, v21, vcc quad_perm:[1,0,3,2] row_mask:0xf bank_mask:0xf
	v_cndmask_b32_e32 v13, v13, v249, vcc
	v_mov_b32_dpp v248, v22 quad_perm:[1,0,3,2] row_mask:0xf bank_mask:0xf
	v_cndmask_b32_dpp v22, v14, v22, vcc quad_perm:[1,0,3,2] row_mask:0xf bank_mask:0xf
	v_cndmask_b32_e32 v14, v14, v248, vcc
	v_mov_b32_dpp v249, v23 quad_perm:[1,0,3,2] row_mask:0xf bank_mask:0xf
	v_cndmask_b32_dpp v23, v15, v23, vcc quad_perm:[1,0,3,2] row_mask:0xf bank_mask:0xf
	v_cndmask_b32_e32 v15, v15, v249, vcc
	v_mov_b32_dpp v248, v4 quad_perm:[1,0,3,2] row_mask:0xf bank_mask:0xf
	v_cndmask_b32_dpp v4, v0, v4, vcc quad_perm:[1,0,3,2] row_mask:0xf bank_mask:0xf
	v_cndmask_b32_e32 v0, v0, v248, vcc
	v_mov_b32_dpp v249, v5 quad_perm:[1,0,3,2] row_mask:0xf bank_mask:0xf
	v_cndmask_b32_dpp v5, v1, v5, vcc quad_perm:[1,0,3,2] row_mask:0xf bank_mask:0xf
	v_cndmask_b32_e32 v1, v1, v249, vcc
	v_mov_b32_dpp v248, v6 quad_perm:[1,0,3,2] row_mask:0xf bank_mask:0xf
	v_cndmask_b32_dpp v6, v2, v6, vcc quad_perm:[1,0,3,2] row_mask:0xf bank_mask:0xf
	v_cndmask_b32_e32 v2, v2, v248, vcc
	v_mov_b32_dpp v249, v7 quad_perm:[1,0,3,2] row_mask:0xf bank_mask:0xf
	v_cndmask_b32_dpp v7, v3, v7, vcc quad_perm:[1,0,3,2] row_mask:0xf bank_mask:0xf
	v_cndmask_b32_e32 v3, v3, v249, vcc
	s_waitcnt vmcnt(0)
; #define EO_LOAD(bt_) do { _Pragma("unroll") for (int mm = 0; mm < 2; ++mm) { const float* xr = xbase + (size_t)(row0 + ((bt_) >> 1) * 128 + (2 * ((bt_) & 1) + mm) * 16) * DM + col0; \
;             _Pragma("unroll") for (int bj = 0; bj < 2; ++bj) _Pragma("unroll") for (int n = 0; n < 2; ++n) xv[(bt_) & 1][mm][bj][n] = *(const f32x4*)(xr + 128 * bj + 4 * n); } } while (0)
; #define EO_FENCE() asm volatile("" ::: "memory")
;     __device__ __forceinline__ void operator()(const f32x4 (&acc)[2][2][4][2], const pg8::Unit& u, int wr, int wc, int fr, int fq) const {
;     ...
;         EO_LOAD(0); EO_FENCE(); EO_LOAD(1); EO_FENCE();
;         EO_STORE(0); EO_FENCE(); EO_LOAD(2); EO_FENCE();
;         EO_STORE(1); EO_FENCE(); EO_LOAD(3); EO_FENCE();
;         EO_STORE(2); EO_FENCE(); EO_STORE(3);
	v_cndmask_b32_e32 v136, v140, v136, vcc
	v_cndmask_b32_e32 v132, v128, v132, vcc
	v_cndmask_b32_e32 v137, v141, v137, vcc
	v_cndmask_b32_e32 v133, v129, v133, vcc
	v_cndmask_b32_e32 v138, v142, v138, vcc
	v_cndmask_b32_e32 v134, v130, v134, vcc
	v_cndmask_b32_e32 v139, v143, v139, vcc
	v_cndmask_b32_e32 v135, v131, v135, vcc
	v_mov_b32_e32 v140, v136
	v_mov_b32_e32 v128, v132
	v_mov_b32_e32 v141, v137
	v_mov_b32_e32 v129, v133
	v_mov_b32_e32 v142, v138
	v_mov_b32_e32 v130, v134
	v_mov_b32_e32 v143, v139
	v_mov_b32_e32 v131, v135
	v_pk_fma_f32 v[122:123], v[122:123], v[142:143], v[174:175]
	v_pk_fma_f32 v[126:127], v[126:127], v[138:139], v[178:179]
	v_pk_fma_f32 v[124:125], v[124:125], v[136:137], v[176:177]
	v_pk_fma_f32 v[120:121], v[120:121], v[140:141], v[172:173]
	v_pk_fma_f32 v[110:111], v[110:111], v[134:135], v[186:187]
	v_pk_fma_f32 v[108:109], v[108:109], v[132:133], v[184:185]
	v_pk_fma_f32 v[106:107], v[106:107], v[130:131], v[182:183]
	v_pk_fma_f32 v[104:105], v[104:105], v[128:129], v[180:181]
	v_pk_fma_f32 v[118:119], v[118:119], v[138:139], v[190:191]
	v_pk_fma_f32 v[116:117], v[116:117], v[136:137], v[188:189]
	v_pk_fma_f32 v[114:115], v[114:115], v[142:143], v[194:195]
	v_pk_fma_f32 v[112:113], v[112:113], v[140:141], v[192:193]
	v_pk_fma_f32 v[102:103], v[102:103], v[134:135], v[198:199]
	v_pk_fma_f32 v[100:101], v[100:101], v[132:133], v[196:197]
	v_pk_fma_f32 v[94:95], v[94:95], v[130:131], v[202:203]
	v_pk_fma_f32 v[92:93], v[92:93], v[128:129], v[200:201]
	global_store_dwordx4 v[242:243], v[124:127], off offset:-2048
	global_store_dwordx4 v[242:243], v[120:123], off offset:2048
	global_store_dwordx4 v[242:243], v[108:111], off offset:-1536
	global_store_dwordx4 v[242:243], v[104:107], off offset:2560
	global_store_dwordx4 v[236:237], v[116:119], off offset:-2048
	global_store_dwordx4 v[236:237], v[112:115], off offset:2048
	global_store_dwordx4 v[236:237], v[100:103], off offset:-1536
	global_store_dwordx4 v[236:237], v[92:95], off offset:2560
	v_lshl_add_u64 v[172:173], v[164:165], 0, s[14:15]
	v_lshl_add_u64 v[174:175], s[66:67], 0, v[238:239]
	v_lshl_add_u64 v[124:125], v[162:163], 0, v[172:173]
	v_lshl_add_u64 v[174:175], v[174:175], 0, v[160:161]
	v_pk_fma_f32 v[74:75], v[74:75], v[130:131], v[218:219]
	v_pk_fma_f32 v[72:73], v[72:73], v[128:129], v[216:217]
	global_load_dwordx4 v[92:95], v[246:247], off offset:2048
	global_load_dwordx4 v[100:103], v[246:247], off offset:-2048
	global_load_dwordx4 v[104:107], v[246:247], off offset:2560
	global_load_dwordx4 v[108:111], v[246:247], off offset:-1536
	global_load_dwordx4 v[112:115], v[124:125], off offset:2048
	global_load_dwordx4 v[116:119], v[124:125], off offset:-2048
	global_load_dwordx4 v[120:123], v[124:125], off offset:2560
	s_nop 0
	global_load_dwordx4 v[124:127], v[124:125], off offset:-1536
	v_pk_fma_f32 v[82:83], v[82:83], v[134:135], v[214:215]
	v_pk_fma_f32 v[80:81], v[80:81], v[132:133], v[212:213]
	global_store_dwordx4 v[174:175], v[72:75], off offset:2560
	global_store_dwordx4 v[174:175], v[80:83], off offset:-1536
	v_pk_fma_f32 v[98:99], v[98:99], v[138:139], v[206:207]
	v_lshl_add_u64 v[72:73], s[66:67], 0, v[240:241]
	v_lshl_add_u64 v[80:81], v[72:73], 0, v[160:161]
	v_pk_fma_f32 v[74:75], v[86:87], v[138:139], v[222:223]
	v_pk_fma_f32 v[72:73], v[84:85], v[136:137], v[220:221]
	v_pk_fma_f32 v[96:97], v[96:97], v[136:137], v[204:205]
	v_pk_fma_f32 v[90:91], v[90:91], v[142:143], v[210:211]
	v_pk_fma_f32 v[88:89], v[88:89], v[140:141], v[208:209]
	global_store_dwordx4 v[80:81], v[72:75], off offset:-2048
	v_pk_fma_f32 v[70:71], v[70:71], v[134:135], v[230:231]
	v_pk_fma_f32 v[68:69], v[68:69], v[132:133], v[228:229]
	v_pk_fma_f32 v[74:75], v[78:79], v[142:143], v[226:227]
	v_pk_fma_f32 v[72:73], v[76:77], v[140:141], v[224:225]
	v_pk_fma_f32 v[66:67], v[66:67], v[130:131], v[234:235]
	v_pk_fma_f32 v[64:65], v[64:65], v[128:129], v[232:233]
	global_store_dwordx4 v[174:175], v[96:99], off offset:-2048
	global_store_dwordx4 v[174:175], v[88:91], off offset:2048
	global_store_dwordx4 v[80:81], v[72:75], off offset:2048
	global_store_dwordx4 v[80:81], v[68:71], off offset:-1536
	global_store_dwordx4 v[80:81], v[64:67], off offset:2560
	v_lshl_add_u64 v[174:175], v[164:165], 0, s[16:17]
	v_lshl_add_u64 v[76:77], v[162:163], 0, v[174:175]
	global_load_dwordx4 v[64:67], v[76:77], off offset:-2048
	global_load_dwordx4 v[68:71], v[76:77], off offset:2048
	global_load_dwordx4 v[72:75], v[76:77], off offset:-1536
	s_nop 0
	global_load_dwordx4 v[76:79], v[76:77], off offset:2560
	v_lshl_add_u64 v[164:165], v[164:165], 0, s[18:19]
	v_lshl_add_u64 v[96:97], v[162:163], 0, v[164:165]
	global_load_dwordx4 v[80:83], v[96:97], off offset:-2048
	global_load_dwordx4 v[84:87], v[96:97], off offset:2048
	global_load_dwordx4 v[88:91], v[96:97], off offset:-1536
	s_nop 0
	global_load_dwordx4 v[96:99], v[96:97], off offset:2560
	v_lshl_add_u64 v[162:163], s[66:67], 0, v[244:245]
	v_lshl_add_u64 v[172:173], s[66:67], 0, v[172:173]
	v_lshl_add_u64 v[174:175], s[66:67], 0, v[174:175]
	v_lshl_add_u64 v[162:163], v[162:163], 0, v[160:161]
	v_lshl_add_u64 v[172:173], v[172:173], 0, v[160:161]
	v_lshl_add_u64 v[174:175], v[174:175], 0, v[160:161]
	s_waitcnt vmcnt(23)
; #define PG8_BAR __builtin_amdgcn_s_barrier()
; #define EO_LOAD(bt_) do { _Pragma("unroll") for (int mm = 0; mm < 2; ++mm) { const float* xr = xbase + (size_t)(row0 + ((bt_) >> 1) * 128 + (2 * ((bt_) & 1) + mm) * 16) * DM + col0; \
;             _Pragma("unroll") for (int bj = 0; bj < 2; ++bj) _Pragma("unroll") for (int n = 0; n < 2; ++n) xv[(bt_) & 1][mm][bj][n] = *(const f32x4*)(xr + 128 * bj + 4 * n); } } while (0)
; #define EO_FENCE() asm volatile("" ::: "memory")
; template <class Epi, class Sched, bool ALIGN_EPI = false, bool SP2 = false>
; __device__ __forceinline__ void gemm_phase(PG8_LAS unsigned char* lds, const Gemm g, const Sched& S, const Epi& E) {
;     ...
;         if (!has_next) break;
; #pragma unroll
;         for (int a = 0; a < 2; ++a)
; #pragma unroll
;             for (int b = 0; b < 2; ++b)
; #pragma unroll
;                 for (int m = 0; m < 4; ++m)
; #pragma unroll
;                     for (int n = 0; n < 2; ++n) acc[a][b][m][n] = (f32x4){0.f, 0.f, 0.f, 0.f};
;         cur = nxt; cA = nA; cB = nB; ++ui;
;         if constexpr (ALIGN_EPI) { if (wr == 1) PG8_BAR; }
;     __device__ __forceinline__ void operator()(const f32x4 (&acc)[2][2][4][2], const pg8::Unit& u, int wr, int wc, int fr, int fq) const {
;     ...
;         EO_LOAD(0); EO_FENCE(); EO_LOAD(1); EO_FENCE();
;         EO_STORE(0); EO_FENCE(); EO_LOAD(2); EO_FENCE();
;         EO_STORE(1); EO_FENCE(); EO_LOAD(3); EO_FENCE();
;         EO_STORE(2); EO_FENCE(); EO_STORE(3);
	v_pk_fma_f32 v[58:59], v[58:59], v[142:143], v[94:95]
	s_waitcnt vmcnt(22)
	v_pk_fma_f32 v[62:63], v[62:63], v[138:139], v[102:103]
	v_pk_fma_f32 v[60:61], v[60:61], v[136:137], v[100:101]
	v_pk_fma_f32 v[56:57], v[56:57], v[140:141], v[92:93]
	s_waitcnt vmcnt(20)
	v_pk_fma_f32 v[46:47], v[46:47], v[134:135], v[110:111]
	v_pk_fma_f32 v[44:45], v[44:45], v[132:133], v[108:109]
	v_pk_fma_f32 v[42:43], v[42:43], v[130:131], v[106:107]
	v_pk_fma_f32 v[40:41], v[40:41], v[128:129], v[104:105]
	s_waitcnt vmcnt(18)
	v_pk_fma_f32 v[54:55], v[54:55], v[138:139], v[118:119]
	v_pk_fma_f32 v[52:53], v[52:53], v[136:137], v[116:117]
	v_pk_fma_f32 v[50:51], v[50:51], v[142:143], v[114:115]
	v_pk_fma_f32 v[48:49], v[48:49], v[140:141], v[112:113]
	s_waitcnt vmcnt(16)
	v_pk_fma_f32 v[34:35], v[34:35], v[134:135], v[126:127]
	v_pk_fma_f32 v[32:33], v[32:33], v[132:133], v[124:125]
	v_pk_fma_f32 v[30:31], v[30:31], v[130:131], v[122:123]
	v_pk_fma_f32 v[28:29], v[28:29], v[128:129], v[120:121]
	global_store_dwordx4 v[162:163], v[60:63], off offset:-2048
	global_store_dwordx4 v[162:163], v[56:59], off offset:2048
	global_store_dwordx4 v[162:163], v[44:47], off offset:-1536
	global_store_dwordx4 v[162:163], v[40:43], off offset:2560
	global_store_dwordx4 v[172:173], v[52:55], off offset:-2048
	global_store_dwordx4 v[172:173], v[48:51], off offset:2048
	global_store_dwordx4 v[172:173], v[32:35], off offset:-1536
	global_store_dwordx4 v[172:173], v[28:31], off offset:2560
	s_waitcnt vmcnt(14)
	v_pk_fma_f32 v[26:27], v[26:27], v[142:143], v[70:71]
	s_waitcnt vmcnt(13)
	v_pk_fma_f32 v[18:19], v[18:19], v[134:135], v[74:75]
	s_waitcnt vmcnt(12)
	v_pk_fma_f32 v[10:11], v[10:11], v[130:131], v[78:79]
	v_pk_fma_f32 v[8:9], v[8:9], v[128:129], v[76:77]
	v_pk_fma_f32 v[16:17], v[16:17], v[132:133], v[72:73]
	global_store_dwordx4 v[174:175], v[8:11], off offset:2560
	global_store_dwordx4 v[174:175], v[16:19], off offset:-1536
	v_pk_fma_f32 v[30:31], v[38:39], v[138:139], v[66:67]
	v_lshl_add_u64 v[8:9], s[66:67], 0, v[164:165]
	v_lshl_add_u64 v[16:17], v[8:9], 0, v[160:161]
	s_waitcnt vmcnt(13)
	v_pk_fma_f32 v[10:11], v[22:23], v[138:139], v[82:83]
	v_pk_fma_f32 v[8:9], v[20:21], v[136:137], v[80:81]
	v_pk_fma_f32 v[28:29], v[36:37], v[136:137], v[64:65]
	v_pk_fma_f32 v[24:25], v[24:25], v[140:141], v[68:69]
	global_store_dwordx4 v[16:17], v[8:11], off offset:-2048
	s_waitcnt vmcnt(12)
	v_pk_fma_f32 v[6:7], v[6:7], v[134:135], v[90:91]
	v_pk_fma_f32 v[4:5], v[4:5], v[132:133], v[88:89]
	v_pk_fma_f32 v[10:11], v[14:15], v[142:143], v[86:87]
	v_pk_fma_f32 v[8:9], v[12:13], v[140:141], v[84:85]
	s_waitcnt vmcnt(11)
	v_pk_fma_f32 v[2:3], v[2:3], v[130:131], v[98:99]
	v_pk_fma_f32 v[0:1], v[0:1], v[128:129], v[96:97]
	global_store_dwordx4 v[174:175], v[28:31], off offset:-2048
	global_store_dwordx4 v[174:175], v[24:27], off offset:2048
	global_store_dwordx4 v[16:17], v[8:11], off offset:2048
	global_store_dwordx4 v[16:17], v[4:7], off offset:-1536
	global_store_dwordx4 v[16:17], v[0:3], off offset:2560
	s_mov_b64 vcc, s[74:75]
	s_cbranch_vccnz .LBB0_453
	s_andn2_b64 vcc, exec, s[4:5]
	s_cbranch_vccnz .LBB0_452
	s_barrier
	s_branch .LBB0_452
